# adds to the widened-store version: P3 first-epilogue stores widened and P6 epilogue Hb loads widened to 16-byte (reverse permlane16_swap) with renamed consumers; checking it does not regress the 1.040
# speedup vs baseline: 1.0413x; 1.0032x over previous
.LBB0_288:
	s_or_b64 exec, exec, s[6:7]
	v_lshl_or_b32 v134, s50, 8, v1
	v_lshl_or_b32 v132, s48, 8, v160
	v_mov_b32_e32 v136, v134
	v_mov_b32_e32 v140, v132
	s_waitcnt vmcnt(0)
	s_barrier
	v_mbcnt_lo_u32_b32 v244, -1, 0
	v_mbcnt_hi_u32_b32 v244, -1, v244
	v_bfe_u32 v244, v244, 4, 1
	v_mul_u32_u24_e32 v244, 24, v244
	v_mov_b32_e32 v245, 0
	s_nop 0
	v_ashrrev_i32_e32 v141, 31, v140
	v_lshlrev_b64 v[138:139], 12, v[140:141]
	v_ashrrev_i32_e32 v137, 31, v136
	v_lshlrev_b64 v[140:141], 11, v[140:141]
	v_lshl_add_u64 v[138:139], s[76:77], 0, v[138:139]
	v_lshlrev_b64 v[136:137], 1, v[136:137]
	v_lshl_add_u64 v[140:141], s[82:83], 0, v[140:141]
	v_lshl_add_u64 v[138:139], v[138:139], 0, v[136:137]
	v_lshl_add_u64 v[136:137], v[140:141], 0, v[136:137]
	global_load_dwordx2 v[140:141], v[138:139], off
	global_load_dwordx2 v[142:143], v[138:139], off offset:32
	global_load_dwordx2 v[144:145], v[138:139], off offset:64
	global_load_dwordx2 v[146:147], v[138:139], off offset:96
	global_load_dwordx2 v[148:149], v[138:139], off offset:256
	global_load_dwordx2 v[150:151], v[138:139], off offset:288
	global_load_dwordx2 v[152:153], v[138:139], off offset:320
	global_load_dwordx2 v[154:155], v[138:139], off offset:352
	v_add_co_u32_e64 v156, s[6:7], s11, v138
	s_waitcnt vmcnt(7)
	v_lshlrev_b32_e32 v130, 16, v140
	v_addc_co_u32_e64 v157, s[6:7], 0, v139, s[6:7]
	global_load_dwordx2 v[158:159], v[156:157], off
	global_load_dwordx2 v[170:171], v[156:157], off offset:32
	global_load_dwordx2 v[172:173], v[156:157], off offset:64
	global_load_dwordx2 v[174:175], v[156:157], off offset:96
	global_load_dwordx2 v[176:177], v[156:157], off offset:256
	global_load_dwordx2 v[178:179], v[156:157], off offset:288
	global_load_dwordx2 v[180:181], v[156:157], off offset:320
	s_nop 0
	global_load_dwordx2 v[156:157], v[156:157], off offset:352
	v_and_b32_e32 v133, 0xffff0000, v140
	v_lshlrev_b32_e32 v135, 16, v141
	v_and_b32_e32 v140, 0xffff0000, v141
	s_waitcnt vmcnt(14)
	v_lshlrev_b32_e32 v141, 16, v142
	v_and_b32_e32 v142, 0xffff0000, v142
	v_lshlrev_b32_e32 v182, 16, v143
	v_and_b32_e32 v143, 0xffff0000, v143
	s_waitcnt vmcnt(13)
	v_lshlrev_b32_e32 v183, 16, v144
	v_and_b32_e32 v144, 0xffff0000, v144
	v_lshlrev_b32_e32 v184, 16, v145
	v_and_b32_e32 v145, 0xffff0000, v145
	s_waitcnt vmcnt(12)
	v_lshlrev_b32_e32 v185, 16, v146
	v_and_b32_e32 v146, 0xffff0000, v146
	v_lshlrev_b32_e32 v186, 16, v147
	v_and_b32_e32 v147, 0xffff0000, v147
	s_waitcnt vmcnt(11)
	v_lshlrev_b32_e32 v187, 16, v148
	v_and_b32_e32 v148, 0xffff0000, v148
	v_lshlrev_b32_e32 v188, 16, v149
	v_and_b32_e32 v149, 0xffff0000, v149
	v_mul_f32_e32 v98, v98, v130
	v_mul_f32_e32 v99, v99, v133
	v_mul_f32_e32 v100, v100, v135
	v_mul_f32_e32 v101, v101, v140
	v_mul_f32_e32 v102, v102, v141
	v_mul_f32_e32 v103, v103, v142
	v_mul_f32_e32 v104, v104, v182
	v_mul_f32_e32 v105, v105, v143
	v_mul_f32_e32 v106, v106, v183
	v_mul_f32_e32 v107, v107, v144
	v_mul_f32_e32 v108, v108, v184
	v_mul_f32_e32 v109, v109, v145
	v_mul_f32_e32 v110, v110, v185
	v_mul_f32_e32 v111, v111, v146
	v_mul_f32_e32 v112, v112, v186
	v_mul_f32_e32 v113, v113, v147
	v_mul_f32_e32 v122, v122, v187
	v_mul_f32_e32 v123, v123, v148
	v_mul_f32_e32 v124, v124, v188
	v_mul_f32_e32 v125, v125, v149
	v_cvt_pk_bf16_f32 v224, v98, v99
	v_cvt_pk_bf16_f32 v225, v100, v101
	v_cvt_pk_bf16_f32 v226, v102, v103
	v_cvt_pk_bf16_f32 v227, v104, v105
	v_cvt_pk_bf16_f32 v228, v106, v107
	v_cvt_pk_bf16_f32 v229, v108, v109
	v_cvt_pk_bf16_f32 v230, v110, v111
	v_cvt_pk_bf16_f32 v231, v112, v113
	v_cvt_pk_bf16_f32 v232, v122, v123
	v_cvt_pk_bf16_f32 v233, v124, v125
	s_nop 1
	v_permlane16_swap_b32_e32 v224, v226
	v_permlane16_swap_b32_e32 v225, v227
	v_permlane16_swap_b32_e32 v228, v230
	v_permlane16_swap_b32_e32 v229, v231
	v_lshl_add_u64 v[240:241], v[136:137], 0, v[244:245]
	global_store_dwordx4 v[240:241], v[224:227], off
	global_store_dwordx4 v[240:241], v[228:231], off offset:64
	s_waitcnt vmcnt(11)
	v_lshlrev_b32_e32 v98, 16, v152
	v_and_b32_e32 v99, 0xffff0000, v152
	v_lshlrev_b32_e32 v100, 16, v153
	v_and_b32_e32 v101, 0xffff0000, v153
	v_mul_f32_e32 v98, v118, v98
	v_mul_f32_e32 v99, v119, v99
	v_mul_f32_e32 v100, v120, v100
	v_mul_f32_e32 v101, v121, v101
	v_cvt_pk_bf16_f32 v236, v98, v99
	v_cvt_pk_bf16_f32 v237, v100, v101
	s_waitcnt vmcnt(10)
	v_lshlrev_b32_e32 v98, 16, v154
	v_and_b32_e32 v99, 0xffff0000, v154
	v_lshlrev_b32_e32 v100, 16, v155
	v_and_b32_e32 v101, 0xffff0000, v155
	v_mul_f32_e32 v98, v114, v98
	v_mul_f32_e32 v99, v115, v99
	v_mul_f32_e32 v100, v116, v100
	v_mul_f32_e32 v101, v117, v101
	v_cvt_pk_bf16_f32 v238, v98, v99
	v_cvt_pk_bf16_f32 v239, v100, v101
	s_waitcnt vmcnt(9)
	v_lshlrev_b32_e32 v98, 16, v158
	v_mul_f32_e32 v94, v94, v98
	v_and_b32_e32 v98, 0xffff0000, v158
	v_mul_f32_e32 v95, v95, v98
	v_lshlrev_b32_e32 v98, 16, v159
	v_mul_f32_e32 v96, v96, v98
	v_and_b32_e32 v98, 0xffff0000, v159
	v_mul_f32_e32 v97, v97, v98
	v_cvt_pk_bf16_f32 v192, v94, v95
	v_cvt_pk_bf16_f32 v193, v96, v97
	v_add_co_u32_e64 v96, s[6:7], s61, v136
	v_lshlrev_b32_e32 v189, 16, v150
	s_nop 0
	v_addc_co_u32_e64 v97, s[6:7], 0, v137, s[6:7]
	s_waitcnt vmcnt(8)
	v_lshlrev_b32_e32 v94, 16, v170
	v_mul_f32_e32 v82, v82, v94
	v_and_b32_e32 v94, 0xffff0000, v170
	v_mul_f32_e32 v83, v83, v94
	v_lshlrev_b32_e32 v94, 16, v171
	v_mul_f32_e32 v84, v84, v94
	v_and_b32_e32 v94, 0xffff0000, v171
	v_mul_f32_e32 v85, v85, v94
	v_cvt_pk_bf16_f32 v194, v82, v83
	v_cvt_pk_bf16_f32 v195, v84, v85
	s_waitcnt vmcnt(7)
	v_lshlrev_b32_e32 v82, 16, v172
	v_mul_f32_e32 v74, v74, v82
	v_and_b32_e32 v82, 0xffff0000, v172
	v_mul_f32_e32 v75, v75, v82
	v_lshlrev_b32_e32 v82, 16, v173
	v_mul_f32_e32 v76, v76, v82
	v_and_b32_e32 v82, 0xffff0000, v173
	v_mul_f32_e32 v77, v77, v82
	v_cvt_pk_bf16_f32 v196, v74, v75
	v_cvt_pk_bf16_f32 v197, v76, v77
	s_waitcnt vmcnt(6)
	v_lshlrev_b32_e32 v74, 16, v174
	v_mul_f32_e32 v66, v66, v74
	v_and_b32_e32 v74, 0xffff0000, v174
	v_mul_f32_e32 v67, v67, v74
	v_lshlrev_b32_e32 v74, 16, v175
	v_mul_f32_e32 v68, v68, v74
	v_and_b32_e32 v74, 0xffff0000, v175
	v_mul_f32_e32 v69, v69, v74
	v_cvt_pk_bf16_f32 v198, v66, v67
	v_cvt_pk_bf16_f32 v199, v68, v69
	s_nop 1
	v_permlane16_swap_b32_e32 v192, v194
	v_permlane16_swap_b32_e32 v193, v195
	v_permlane16_swap_b32_e32 v196, v198
	v_permlane16_swap_b32_e32 v197, v199
	v_lshl_add_u64 v[240:241], v[96:97], 0, v[244:245]
	global_store_dwordx4 v[240:241], v[192:195], off
	global_store_dwordx4 v[240:241], v[196:199], off offset:64
	s_waitcnt vmcnt(7)
	v_lshlrev_b32_e32 v66, 16, v176
	v_and_b32_e32 v67, 0xffff0000, v176
	v_lshlrev_b32_e32 v68, 16, v177
	v_and_b32_e32 v69, 0xffff0000, v177
	v_mul_f32_e32 v66, v90, v66
	v_mul_f32_e32 v67, v91, v67
	v_mul_f32_e32 v68, v92, v68
	v_mul_f32_e32 v69, v93, v69
	v_cvt_pk_bf16_f32 v200, v66, v67
	v_cvt_pk_bf16_f32 v201, v68, v69
	s_waitcnt vmcnt(6)
	v_lshlrev_b32_e32 v66, 16, v178
	v_and_b32_e32 v67, 0xffff0000, v178
	v_lshlrev_b32_e32 v68, 16, v179
	v_and_b32_e32 v69, 0xffff0000, v179
	v_mul_f32_e32 v66, v86, v66
	v_mul_f32_e32 v67, v87, v67
	v_mul_f32_e32 v68, v88, v68
	v_mul_f32_e32 v69, v89, v69
	v_cvt_pk_bf16_f32 v202, v66, v67
	v_cvt_pk_bf16_f32 v203, v68, v69
	s_waitcnt vmcnt(5)
	v_lshlrev_b32_e32 v66, 16, v180
	v_and_b32_e32 v67, 0xffff0000, v180
	v_lshlrev_b32_e32 v68, 16, v181
	v_and_b32_e32 v69, 0xffff0000, v181
	v_mul_f32_e32 v66, v78, v66
	v_mul_f32_e32 v67, v79, v67
	v_mul_f32_e32 v68, v80, v68
	v_mul_f32_e32 v69, v81, v69
	v_cvt_pk_bf16_f32 v204, v66, v67
	v_cvt_pk_bf16_f32 v205, v68, v69
	v_and_b32_e32 v150, 0xffff0000, v150
	v_lshlrev_b32_e32 v190, 16, v151
	v_and_b32_e32 v151, 0xffff0000, v151
	s_waitcnt vmcnt(4)
	v_lshlrev_b32_e32 v66, 16, v156
	v_and_b32_e32 v67, 0xffff0000, v156
	v_lshlrev_b32_e32 v68, 16, v157
	v_and_b32_e32 v69, 0xffff0000, v157
	v_mul_f32_e32 v126, v126, v189
	v_mul_f32_e32 v127, v127, v150
	v_mul_f32_e32 v128, v128, v190
	v_mul_f32_e32 v129, v129, v151
	v_mul_f32_e32 v66, v70, v66
	v_mul_f32_e32 v67, v71, v67
	v_mul_f32_e32 v68, v72, v68
	v_mul_f32_e32 v69, v73, v69
	v_cvt_pk_bf16_f32 v234, v126, v127
	v_cvt_pk_bf16_f32 v235, v128, v129
	v_cvt_pk_bf16_f32 v206, v66, v67
	v_cvt_pk_bf16_f32 v207, v68, v69
	s_nop 1
	v_permlane16_swap_b32_e32 v232, v234
	v_permlane16_swap_b32_e32 v233, v235
	v_permlane16_swap_b32_e32 v236, v238
	v_permlane16_swap_b32_e32 v237, v239
	v_lshl_add_u64 v[240:241], v[136:137], 0, v[244:245]
	global_store_dwordx4 v[240:241], v[232:235], off offset:256
	global_store_dwordx4 v[240:241], v[236:239], off offset:320
	s_nop 1
	v_permlane16_swap_b32_e32 v200, v202
	v_permlane16_swap_b32_e32 v201, v203
	v_permlane16_swap_b32_e32 v204, v206
	v_permlane16_swap_b32_e32 v205, v207
	v_lshl_add_u64 v[240:241], v[96:97], 0, v[244:245]
	global_store_dwordx4 v[240:241], v[200:203], off offset:256
	global_store_dwordx4 v[240:241], v[204:207], off offset:320
	v_add_co_u32_e64 v66, s[6:7], s62, v138
	s_mov_b32 s0, s48
	s_nop 0
	v_addc_co_u32_e64 v67, s[6:7], 0, v139, s[6:7]
	global_load_dwordx2 v[68:69], v[66:67], off
	global_load_dwordx2 v[70:71], v[66:67], off offset:32
	global_load_dwordx2 v[72:73], v[66:67], off offset:64
	global_load_dwordx2 v[74:75], v[66:67], off offset:96
	global_load_dwordx2 v[76:77], v[66:67], off offset:256
	global_load_dwordx2 v[78:79], v[66:67], off offset:288
	global_load_dwordx2 v[82:83], v[66:67], off offset:320
	v_add_co_u32_e64 v80, s[6:7], s63, v138
	s_waitcnt vmcnt(6)
	v_lshlrev_b32_e32 v100, 16, v68
	v_addc_co_u32_e64 v81, s[6:7], 0, v139, s[6:7]
	global_load_dwordx2 v[66:67], v[66:67], off offset:352
	s_nop 0
	global_load_dwordx2 v[86:87], v[80:81], off
	global_load_dwordx2 v[88:89], v[80:81], off offset:32
	global_load_dwordx2 v[90:91], v[80:81], off offset:64
	global_load_dwordx2 v[92:93], v[80:81], off offset:96
	global_load_dwordx2 v[94:95], v[80:81], off offset:256
	global_load_dwordx2 v[96:97], v[80:81], off offset:288
	global_load_dwordx2 v[98:99], v[80:81], off offset:320
	s_nop 0
	global_load_dwordx2 v[80:81], v[80:81], off offset:352
	v_and_b32_e32 v68, 0xffff0000, v68
	v_lshlrev_b32_e32 v101, 16, v69
	v_and_b32_e32 v69, 0xffff0000, v69
	s_waitcnt vmcnt(14)
	v_lshlrev_b32_e32 v102, 16, v70
	v_and_b32_e32 v70, 0xffff0000, v70
	v_add_co_u32_e64 v84, s[6:7], s64, v136
	v_lshlrev_b32_e32 v103, 16, v71
	v_and_b32_e32 v71, 0xffff0000, v71
	s_waitcnt vmcnt(13)
	v_lshlrev_b32_e32 v104, 16, v72
	v_and_b32_e32 v72, 0xffff0000, v72
	v_lshlrev_b32_e32 v105, 16, v73
	v_and_b32_e32 v73, 0xffff0000, v73
	s_waitcnt vmcnt(12)
	v_lshlrev_b32_e32 v106, 16, v74
	v_and_b32_e32 v74, 0xffff0000, v74
	v_lshlrev_b32_e32 v107, 16, v75
	v_and_b32_e32 v75, 0xffff0000, v75
	s_waitcnt vmcnt(11)
	v_lshlrev_b32_e32 v108, 16, v76
	v_and_b32_e32 v76, 0xffff0000, v76
	v_lshlrev_b32_e32 v109, 16, v77
	v_and_b32_e32 v77, 0xffff0000, v77
	v_mul_f32_e32 v38, v38, v100
	v_mul_f32_e32 v39, v39, v68
	v_mul_f32_e32 v40, v40, v101
	v_mul_f32_e32 v41, v41, v69
	v_mul_f32_e32 v42, v42, v102
	v_mul_f32_e32 v43, v43, v70
	v_addc_co_u32_e64 v85, s[6:7], 0, v137, s[6:7]
	v_mul_f32_e32 v44, v44, v103
	v_mul_f32_e32 v45, v45, v71
	v_mul_f32_e32 v46, v46, v104
	v_mul_f32_e32 v47, v47, v72
	v_mul_f32_e32 v48, v48, v105
	v_mul_f32_e32 v49, v49, v73
	v_mul_f32_e32 v50, v50, v106
	v_mul_f32_e32 v51, v51, v74
	v_mul_f32_e32 v52, v52, v107
	v_mul_f32_e32 v53, v53, v75
	v_mul_f32_e32 v62, v62, v108
	v_mul_f32_e32 v63, v63, v76
	v_mul_f32_e32 v64, v64, v109
	v_mul_f32_e32 v65, v65, v77
	v_cvt_pk_bf16_f32 v208, v38, v39
	v_cvt_pk_bf16_f32 v209, v40, v41
	v_cvt_pk_bf16_f32 v210, v42, v43
	s_waitcnt vmcnt(10)
	v_lshlrev_b32_e32 v110, 16, v78
	v_cvt_pk_bf16_f32 v211, v44, v45
	v_cvt_pk_bf16_f32 v212, v46, v47
	v_cvt_pk_bf16_f32 v213, v48, v49
	v_cvt_pk_bf16_f32 v214, v50, v51
	v_cvt_pk_bf16_f32 v215, v52, v53
	v_cvt_pk_bf16_f32 v224, v62, v63
	v_cvt_pk_bf16_f32 v225, v64, v65
	s_nop 1
	v_permlane16_swap_b32_e32 v208, v210
	v_permlane16_swap_b32_e32 v209, v211
	v_permlane16_swap_b32_e32 v212, v214
	v_permlane16_swap_b32_e32 v213, v215
	v_lshl_add_u64 v[240:241], v[84:85], 0, v[244:245]
	global_store_dwordx4 v[240:241], v[208:211], off
	global_store_dwordx4 v[240:241], v[212:215], off offset:64
	v_and_b32_e32 v38, 0xffff0000, v78
	v_lshlrev_b32_e32 v39, 16, v79
	v_and_b32_e32 v40, 0xffff0000, v79
	v_mul_f32_e32 v58, v58, v110
	v_mul_f32_e32 v38, v59, v38
	v_mul_f32_e32 v39, v60, v39
	v_mul_f32_e32 v40, v61, v40
	v_cvt_pk_bf16_f32 v226, v58, v38
	v_cvt_pk_bf16_f32 v227, v39, v40
	s_waitcnt vmcnt(11)
	v_lshlrev_b32_e32 v38, 16, v82
	v_and_b32_e32 v39, 0xffff0000, v82
	v_lshlrev_b32_e32 v40, 16, v83
	v_and_b32_e32 v41, 0xffff0000, v83
	v_mul_f32_e32 v38, v54, v38
	v_mul_f32_e32 v39, v55, v39
	v_mul_f32_e32 v40, v56, v40
	v_mul_f32_e32 v41, v57, v41
	v_cvt_pk_bf16_f32 v228, v38, v39
	v_cvt_pk_bf16_f32 v229, v40, v41
	s_waitcnt vmcnt(10)
	v_lshlrev_b32_e32 v38, 16, v66
	v_mul_f32_e32 v34, v34, v38
	v_and_b32_e32 v38, 0xffff0000, v66
	v_mul_f32_e32 v35, v35, v38
	v_lshlrev_b32_e32 v38, 16, v67
	v_mul_f32_e32 v36, v36, v38
	v_and_b32_e32 v38, 0xffff0000, v67
	v_mul_f32_e32 v37, v37, v38
	v_cvt_pk_bf16_f32 v230, v34, v35
	v_cvt_pk_bf16_f32 v231, v36, v37
	s_nop 1
	v_permlane16_swap_b32_e32 v224, v226
	v_permlane16_swap_b32_e32 v225, v227
	v_permlane16_swap_b32_e32 v228, v230
	v_permlane16_swap_b32_e32 v229, v231
	v_lshl_add_u64 v[240:241], v[84:85], 0, v[244:245]
	global_store_dwordx4 v[240:241], v[224:227], off offset:256
	global_store_dwordx4 v[240:241], v[228:231], off offset:320
	s_waitcnt vmcnt(11)
	v_lshlrev_b32_e32 v34, 16, v86
	v_mul_f32_e32 v30, v30, v34
	v_and_b32_e32 v34, 0xffff0000, v86
	v_mul_f32_e32 v31, v31, v34
	v_lshlrev_b32_e32 v34, 16, v87
	v_mul_f32_e32 v32, v32, v34
	v_and_b32_e32 v34, 0xffff0000, v87
	v_mul_f32_e32 v33, v33, v34
	v_cvt_pk_bf16_f32 v232, v30, v31
	v_cvt_pk_bf16_f32 v233, v32, v33
	v_add_co_u32_e64 v32, s[6:7], s65, v136
	s_nop 1
	v_addc_co_u32_e64 v33, s[6:7], 0, v137, s[6:7]
	s_waitcnt vmcnt(10)
	v_lshlrev_b32_e32 v30, 16, v88
	v_mul_f32_e32 v22, v22, v30
	v_and_b32_e32 v30, 0xffff0000, v88
	v_mul_f32_e32 v23, v23, v30
	v_lshlrev_b32_e32 v30, 16, v89
	v_mul_f32_e32 v24, v24, v30
	v_and_b32_e32 v30, 0xffff0000, v89
	v_mul_f32_e32 v25, v25, v30
	v_cvt_pk_bf16_f32 v234, v22, v23
	v_cvt_pk_bf16_f32 v235, v24, v25
	s_waitcnt vmcnt(9)
	v_lshlrev_b32_e32 v22, 16, v90
	v_mul_f32_e32 v14, v14, v22
	v_and_b32_e32 v22, 0xffff0000, v90
	v_mul_f32_e32 v15, v15, v22
	v_lshlrev_b32_e32 v22, 16, v91
	v_mul_f32_e32 v16, v16, v22
	v_and_b32_e32 v22, 0xffff0000, v91
	v_mul_f32_e32 v17, v17, v22
	v_cvt_pk_bf16_f32 v236, v14, v15
	v_cvt_pk_bf16_f32 v237, v16, v17
	s_waitcnt vmcnt(8)
	v_lshlrev_b32_e32 v14, 16, v92
	v_mul_f32_e32 v6, v6, v14
	v_and_b32_e32 v14, 0xffff0000, v92
	v_mul_f32_e32 v7, v7, v14
	v_lshlrev_b32_e32 v14, 16, v93
	v_mul_f32_e32 v8, v8, v14
	v_and_b32_e32 v14, 0xffff0000, v93
	v_mul_f32_e32 v9, v9, v14
	v_cvt_pk_bf16_f32 v238, v6, v7
	v_cvt_pk_bf16_f32 v239, v8, v9
	s_nop 1
	v_permlane16_swap_b32_e32 v232, v234
	v_permlane16_swap_b32_e32 v233, v235
	v_permlane16_swap_b32_e32 v236, v238
	v_permlane16_swap_b32_e32 v237, v239
	v_lshl_add_u64 v[240:241], v[32:33], 0, v[244:245]
	global_store_dwordx4 v[240:241], v[232:235], off
	global_store_dwordx4 v[240:241], v[236:239], off offset:64
	s_waitcnt vmcnt(9)
	v_lshlrev_b32_e32 v6, 16, v94
	v_and_b32_e32 v7, 0xffff0000, v94
	v_lshlrev_b32_e32 v8, 16, v95
	v_and_b32_e32 v9, 0xffff0000, v95
	v_mul_f32_e32 v6, v26, v6
	v_mul_f32_e32 v7, v27, v7
	v_mul_f32_e32 v8, v28, v8
	v_mul_f32_e32 v9, v29, v9
	v_cvt_pk_bf16_f32 v192, v6, v7
	v_cvt_pk_bf16_f32 v193, v8, v9
	s_waitcnt vmcnt(8)
	v_lshlrev_b32_e32 v6, 16, v96
	v_and_b32_e32 v7, 0xffff0000, v96
	v_lshlrev_b32_e32 v8, 16, v97
	v_and_b32_e32 v9, 0xffff0000, v97
	v_mul_f32_e32 v6, v18, v6
	v_mul_f32_e32 v7, v19, v7
	v_mul_f32_e32 v8, v20, v8
	v_mul_f32_e32 v9, v21, v9
	v_cvt_pk_bf16_f32 v194, v6, v7
	v_cvt_pk_bf16_f32 v195, v8, v9
	s_waitcnt vmcnt(7)
	v_lshlrev_b32_e32 v6, 16, v98
	v_and_b32_e32 v7, 0xffff0000, v98
	v_lshlrev_b32_e32 v8, 16, v99
	v_and_b32_e32 v9, 0xffff0000, v99
	v_mul_f32_e32 v6, v10, v6
	v_mul_f32_e32 v7, v11, v7
	v_mul_f32_e32 v8, v12, v8
	v_mul_f32_e32 v9, v13, v9
	v_cvt_pk_bf16_f32 v196, v6, v7
	v_cvt_pk_bf16_f32 v197, v8, v9
	s_waitcnt vmcnt(6)
	v_lshlrev_b32_e32 v6, 16, v80
	v_mul_f32_e32 v2, v2, v6
	v_and_b32_e32 v6, 0xffff0000, v80
	v_mul_f32_e32 v3, v3, v6
	v_lshlrev_b32_e32 v6, 16, v81
	v_mul_f32_e32 v4, v4, v6
	v_and_b32_e32 v6, 0xffff0000, v81
	v_mul_f32_e32 v5, v5, v6
	v_cvt_pk_bf16_f32 v198, v2, v3
	v_cvt_pk_bf16_f32 v199, v4, v5
	s_nop 1
	v_permlane16_swap_b32_e32 v192, v194
	v_permlane16_swap_b32_e32 v193, v195
	v_permlane16_swap_b32_e32 v196, v198
	v_permlane16_swap_b32_e32 v197, v199
	v_lshl_add_u64 v[240:241], v[32:33], 0, v[244:245]
	global_store_dwordx4 v[240:241], v[192:195], off offset:256
	global_store_dwordx4 v[240:241], v[196:199], off offset:320
	v_mov_b32_e32 v2, v0
	s_ashr_i32 s51, s50, 31
	v_lshlrev_b32_e32 v3, 4, v2
	v_bfe_i32 v2, v2, 27, 1
	v_lshrrev_b32_e32 v2, 22, v2
	v_add_u32_e32 v2, v3, v2
	v_ashrrev_i32_e32 v10, 10, v2
	v_mul_i32_i24_e32 v2, 0x400, v10
	v_sub_u32_e32 v2, v3, v2
	v_add_u32_e32 v4, 0x2000, v3
	v_lshrrev_b32_e32 v3, 4, v2
	v_bitop3_b32 v2, v3, v2, 32 bitop3:0x6c
	v_ashrrev_i32_e32 v5, 31, v2
	v_lshrrev_b32_e32 v5, 26, v5
	v_add_u32_e32 v5, v2, v5
	v_ashrrev_i32_e32 v12, 6, v5
	v_and_b32_e32 v5, 0xc0, v5
	v_sub_u32_e32 v2, v2, v5
	v_ashrrev_i16_sdwa v14, v169, sext(v2) dst_sel:DWORD dst_unused:UNUSED_PAD src0_sel:DWORD src1_sel:BYTE_0
	v_ashrrev_i32_e32 v2, 31, v4
	v_lshrrev_b32_e32 v2, 22, v2
	v_add_u32_e32 v2, v4, v2
	v_ashrrev_i32_e32 v11, 10, v2
	v_mul_i32_i24_e32 v2, 0x400, v11
	v_sub_u32_e32 v2, v4, v2
	v_lshrrev_b32_e32 v4, 4, v2
	v_bitop3_b32 v2, v4, v2, 32 bitop3:0x6c
	s_lshl_b64 s[50:51], s[50:51], 19
	v_ashrrev_i32_e32 v5, 31, v2
	s_add_u32 s6, s38, s50
	v_lshrrev_b32_e32 v5, 26, v5
	s_addc_u32 s7, s39, s51
	s_ashr_i32 s1, s0, 31
	v_lshlrev_b32_e32 v3, 3, v10
	v_add_u32_e32 v5, v2, v5
	s_lshl_b64 s[54:55], s[0:1], 19
	v_and_b32_e32 v3, 0x3ffff0, v3
	v_lshlrev_b32_e32 v6, 5, v10
	v_lshlrev_b32_e32 v4, 3, v11
	v_ashrrev_i32_e32 v15, 6, v5
	v_and_b32_e32 v5, 0xc0, v5
	s_add_u32 s56, s80, s54
	v_readfirstlane_b32 s0, v0
	v_add_u32_e32 v3, v12, v3
	v_and_b32_e32 v13, 32, v6
	v_and_b32_e32 v4, 0x3ffff0, v4
	v_lshlrev_b32_e32 v6, 5, v11
	v_sub_u32_e32 v2, v2, v5
	s_addc_u32 s57, s81, s55
	s_lshl_b32 s0, s0, 4
	v_add_u32_e32 v4, v15, v4
	v_and_b32_e32 v16, 32, v6
	v_ashrrev_i16_sdwa v17, v169, sext(v2) dst_sel:DWORD dst_unused:UNUSED_PAD src0_sel:DWORD src1_sel:BYTE_0
	v_lshl_or_b32 v2, v3, 10, v13
	v_lshl_or_b32 v3, v4, 10, v16
	s_and_b32 s49, s0, 0xfffffc00
	v_add_u32_sdwa v130, v2, sext(v14) dst_sel:DWORD dst_unused:UNUSED_PAD src0_sel:DWORD src1_sel:WORD_0
	v_add_u32_sdwa v136, v3, sext(v17) dst_sel:DWORD dst_unused:UNUSED_PAD src0_sel:DWORD src1_sel:WORD_0
	v_lshlrev_b64 v[18:19], 1, v[130:131]
	s_add_i32 s67, s49, 0x10000
	v_mov_b32_e32 v137, v131
	v_lshl_add_u64 v[2:3], s[56:57], 0, v[18:19]
	s_mov_b32 m0, s67
	v_lshlrev_b64 v[20:21], 1, v[136:137]
	s_add_i32 s68, s49, 0x12000
	global_load_lds_dwordx4 v[2:3], off
	v_lshl_add_u64 v[6:7], s[56:57], 0, v[20:21]
	s_mov_b32 m0, s68
	s_add_i32 s69, s49, 0x2000
	global_load_lds_dwordx4 v[6:7], off
	v_lshl_add_u64 v[8:9], s[6:7], 0, v[18:19]
	s_mov_b32 m0, s49
	s_add_u32 s0, s56, 0x40000
	global_load_lds_dwordx4 v[8:9], off
	v_lshl_add_u64 v[4:5], s[6:7], 0, v[20:21]
	s_mov_b32 m0, s69
	s_addc_u32 s1, s57, 0
	s_add_i32 s70, s49, 0x14000
	global_load_lds_dwordx4 v[4:5], off
	v_lshl_add_u64 v[22:23], s[0:1], 0, v[18:19]
	s_mov_b32 m0, s70
	s_add_i32 s71, s49, 0x16000
	global_load_lds_dwordx4 v[22:23], off
	v_lshl_add_u64 v[22:23], s[0:1], 0, v[20:21]
	s_add_u32 s0, s6, 0x40000
	s_mov_b32 m0, s71
	s_addc_u32 s1, s7, 0
	s_add_i32 s72, s49, 0x4000
	global_load_lds_dwordx4 v[22:23], off
	v_lshl_add_u64 v[18:19], s[0:1], 0, v[18:19]
	s_mov_b32 m0, s72
	s_add_i32 s73, s49, 0x6000
	global_load_lds_dwordx4 v[18:19], off
	v_lshl_add_u64 v[18:19], s[0:1], 0, v[20:21]
	s_mov_b32 m0, s73
	s_nop 0
	global_load_lds_dwordx4 v[18:19], off
	s_and_saveexec_b64 s[58:59], vcc
	s_cbranch_execz .LBB0_290
	s_barrier

.LBB0_394:
	s_or_b64 exec, exec, s[22:23]
	v_lshl_or_b32 v132, s31, 8, v142
	v_lshl_or_b32 v136, s33, 8, v1
	s_waitcnt vmcnt(0)
	s_barrier
	v_mbcnt_lo_u32_b32 v210, -1, 0
	v_mbcnt_hi_u32_b32 v210, -1, v210
	v_bfe_u32 v210, v210, 4, 1
	v_mul_u32_u24_e32 v210, 24, v210
	v_mov_b32_e32 v211, 0
	v_readlane_b32 s48, v249, 16
	v_ashrrev_i32_e32 v133, 31, v132
	v_ashrrev_i32_e32 v137, 31, v136
	v_lshlrev_b64 v[134:135], 11, v[132:133]
	v_lshl_add_u64 v[138:139], s[12:13], 0, v[134:135]
	v_lshlrev_b64 v[134:135], 1, v[136:137]
	v_lshl_add_u64 v[138:139], v[138:139], 0, v[134:135]
	v_lshl_add_u64 v[208:209], v[138:139], 0, v[210:211]
	global_load_dwordx4 v[192:195], v[208:209], off
	global_load_dwordx4 v[196:199], v[208:209], off offset:64
	v_lshl_add_u64 v[208:209], v[138:139], 0, v[210:211]
	global_load_dwordx4 v[200:203], v[208:209], off offset:256
	global_load_dwordx4 v[204:207], v[208:209], off offset:320
	s_nop 0
	v_add_u32_e32 v164, 16, v132
	v_readlane_b32 s60, v249, 28
	v_readlane_b32 s61, v249, 29
	v_lshlrev_b64 v[166:167], 12, v[132:133]
	v_ashrrev_i32_e32 v165, 31, v164
	s_mov_b64 s[24:25], s[60:61]
	v_lshlrev_b64 v[136:137], 2, v[136:137]
	v_lshl_add_u64 v[166:167], s[24:25], 0, v[166:167]
	v_lshlrev_b64 v[168:169], 11, v[164:165]
	v_lshl_add_u64 v[166:167], v[166:167], 0, v[136:137]
	v_lshl_add_u64 v[168:169], s[12:13], 0, v[168:169]
	v_lshl_add_u64 v[168:169], v[168:169], 0, v[134:135]
	v_readlane_b32 s49, v249, 17
	v_readlane_b32 s50, v249, 18
	v_readlane_b32 s51, v249, 19
	v_readlane_b32 s52, v249, 20
	v_readlane_b32 s53, v249, 21
	v_readlane_b32 s54, v249, 22
	v_readlane_b32 s55, v249, 23
	v_readlane_b32 s56, v249, 24
	v_readlane_b32 s57, v249, 25
	v_readlane_b32 s58, v249, 26
	v_readlane_b32 s59, v249, 27
	v_readlane_b32 s62, v249, 30
	v_readlane_b32 s63, v249, 31
	s_waitcnt vmcnt(3)
	v_permlane16_swap_b32_e32 v192, v194
	v_permlane16_swap_b32_e32 v193, v195
	v_lshlrev_b32_e32 v170, 16, v192
	v_and_b32_e32 v171, 0xffff0000, v192
	v_lshlrev_b32_e32 v140, 16, v193
	v_and_b32_e32 v141, 0xffff0000, v193
	s_waitcnt vmcnt(3)
	v_lshlrev_b32_e32 v172, 16, v194
	v_and_b32_e32 v173, 0xffff0000, v194
	v_lshlrev_b32_e32 v152, 16, v195
	v_and_b32_e32 v153, 0xffff0000, v195
	s_waitcnt vmcnt(2)
	v_permlane16_swap_b32_e32 v196, v198
	v_permlane16_swap_b32_e32 v197, v199
	v_lshlrev_b32_e32 v174, 16, v196
	v_and_b32_e32 v175, 0xffff0000, v196
	v_lshlrev_b32_e32 v154, 16, v197
	v_and_b32_e32 v155, 0xffff0000, v197
	s_waitcnt vmcnt(2)
	v_lshlrev_b32_e32 v176, 16, v198
	v_and_b32_e32 v177, 0xffff0000, v198
	v_lshlrev_b32_e32 v156, 16, v199
	v_and_b32_e32 v157, 0xffff0000, v199
	s_waitcnt vmcnt(1)
	v_permlane16_swap_b32_e32 v200, v202
	v_permlane16_swap_b32_e32 v201, v203
	v_lshlrev_b32_e32 v178, 16, v200
	v_and_b32_e32 v179, 0xffff0000, v200
	v_lshlrev_b32_e32 v158, 16, v201
	v_and_b32_e32 v159, 0xffff0000, v201
	s_waitcnt vmcnt(1)
	v_lshlrev_b32_e32 v180, 16, v202
	v_and_b32_e32 v181, 0xffff0000, v202
	v_lshlrev_b32_e32 v160, 16, v203
	v_and_b32_e32 v161, 0xffff0000, v203
	s_waitcnt vmcnt(0)
	v_permlane16_swap_b32_e32 v204, v206
	v_permlane16_swap_b32_e32 v205, v207
	v_lshlrev_b32_e32 v182, 16, v204
	v_and_b32_e32 v183, 0xffff0000, v204
	v_lshlrev_b32_e32 v162, 16, v205
	v_and_b32_e32 v163, 0xffff0000, v205
	s_waitcnt vmcnt(0)
	v_lshlrev_b32_e32 v184, 16, v206
	v_and_b32_e32 v185, 0xffff0000, v206
	v_lshlrev_b32_e32 v138, 16, v207
	v_and_b32_e32 v139, 0xffff0000, v207
	v_pk_add_f32 v[98:99], v[98:99], v[170:171]
	v_pk_add_f32 v[100:101], v[100:101], v[140:141]
	v_pk_add_f32 v[102:103], v[102:103], v[172:173]
	v_pk_add_f32 v[104:105], v[104:105], v[152:153]
	v_pk_add_f32 v[106:107], v[106:107], v[174:175]
	v_pk_add_f32 v[108:109], v[108:109], v[154:155]
	v_pk_add_f32 v[110:111], v[110:111], v[176:177]
	v_pk_add_f32 v[112:113], v[112:113], v[156:157]
	v_pk_add_f32 v[114:115], v[114:115], v[178:179]
	v_pk_add_f32 v[116:117], v[116:117], v[158:159]
	v_pk_add_f32 v[118:119], v[118:119], v[180:181]
	v_pk_add_f32 v[120:121], v[120:121], v[160:161]
	v_pk_add_f32 v[122:123], v[122:123], v[182:183]
	v_pk_add_f32 v[124:125], v[124:125], v[162:163]
	v_pk_add_f32 v[126:127], v[126:127], v[184:185]
	v_pk_add_f32 v[128:129], v[128:129], v[138:139]
	global_store_dwordx4 v[166:167], v[98:101], off
	global_store_dwordx4 v[166:167], v[102:105], off offset:64
	global_store_dwordx4 v[166:167], v[106:109], off offset:128
	global_store_dwordx4 v[166:167], v[110:113], off offset:192
	global_store_dwordx4 v[166:167], v[114:117], off offset:512
	global_store_dwordx4 v[166:167], v[118:121], off offset:576
	global_store_dwordx4 v[166:167], v[122:125], off offset:640
	global_store_dwordx4 v[166:167], v[126:129], off offset:704
	v_lshl_add_u64 v[208:209], v[168:169], 0, v[210:211]
	global_load_dwordx4 v[192:195], v[208:209], off
	global_load_dwordx4 v[196:199], v[208:209], off offset:64
	v_lshl_add_u64 v[208:209], v[168:169], 0, v[210:211]
	global_load_dwordx4 v[200:203], v[208:209], off offset:256
	global_load_dwordx4 v[204:207], v[208:209], off offset:320
	v_add_u32_e32 v114, 0x80, v132
	v_ashrrev_i32_e32 v115, 31, v114
	v_lshlrev_b64 v[116:117], 12, v[164:165]
	v_lshlrev_b64 v[118:119], 11, v[114:115]
	v_lshl_add_u64 v[116:117], s[24:25], 0, v[116:117]
	v_lshl_add_u64 v[118:119], s[12:13], 0, v[118:119]
	v_lshl_add_u64 v[116:117], v[116:117], 0, v[136:137]
	v_lshl_add_u64 v[118:119], v[118:119], 0, v[134:135]
	s_waitcnt vmcnt(3)
	v_permlane16_swap_b32_e32 v192, v194
	v_permlane16_swap_b32_e32 v193, v195
	v_lshlrev_b32_e32 v120, 16, v192
	v_and_b32_e32 v121, 0xffff0000, v192
	v_lshlrev_b32_e32 v98, 16, v193
	v_and_b32_e32 v99, 0xffff0000, v193
	s_waitcnt vmcnt(3)
	v_lshlrev_b32_e32 v122, 16, v194
	v_and_b32_e32 v123, 0xffff0000, v194
	v_lshlrev_b32_e32 v100, 16, v195
	v_and_b32_e32 v101, 0xffff0000, v195
	s_waitcnt vmcnt(2)
	v_permlane16_swap_b32_e32 v196, v198
	v_permlane16_swap_b32_e32 v197, v199
	v_lshlrev_b32_e32 v124, 16, v196
	v_and_b32_e32 v125, 0xffff0000, v196
	v_lshlrev_b32_e32 v102, 16, v197
	v_and_b32_e32 v103, 0xffff0000, v197
	s_waitcnt vmcnt(2)
	v_lshlrev_b32_e32 v126, 16, v198
	v_and_b32_e32 v127, 0xffff0000, v198
	v_lshlrev_b32_e32 v104, 16, v199
	v_and_b32_e32 v105, 0xffff0000, v199
	s_waitcnt vmcnt(1)
	v_permlane16_swap_b32_e32 v200, v202
	v_permlane16_swap_b32_e32 v201, v203
	v_lshlrev_b32_e32 v128, 16, v200
	v_and_b32_e32 v129, 0xffff0000, v200
	v_lshlrev_b32_e32 v106, 16, v201
	v_and_b32_e32 v107, 0xffff0000, v201
	s_waitcnt vmcnt(1)
	v_lshlrev_b32_e32 v138, 16, v202
	v_and_b32_e32 v139, 0xffff0000, v202
	v_lshlrev_b32_e32 v108, 16, v203
	v_and_b32_e32 v109, 0xffff0000, v203
	s_waitcnt vmcnt(0)
	v_permlane16_swap_b32_e32 v204, v206
	v_permlane16_swap_b32_e32 v205, v207
	v_lshlrev_b32_e32 v140, 16, v204
	v_and_b32_e32 v141, 0xffff0000, v204
	v_lshlrev_b32_e32 v110, 16, v205
	v_and_b32_e32 v111, 0xffff0000, v205
	s_waitcnt vmcnt(0)
	v_lshlrev_b32_e32 v152, 16, v206
	v_and_b32_e32 v153, 0xffff0000, v206
	v_lshlrev_b32_e32 v112, 16, v207
	v_and_b32_e32 v113, 0xffff0000, v207
	v_pk_add_f32 v[66:67], v[66:67], v[120:121]
	v_pk_add_f32 v[68:69], v[68:69], v[98:99]
	v_pk_add_f32 v[70:71], v[70:71], v[122:123]
	v_pk_add_f32 v[72:73], v[72:73], v[100:101]
	v_pk_add_f32 v[74:75], v[74:75], v[124:125]
	v_pk_add_f32 v[76:77], v[76:77], v[102:103]
	v_pk_add_f32 v[78:79], v[78:79], v[126:127]
	v_pk_add_f32 v[80:81], v[80:81], v[104:105]
	v_pk_add_f32 v[82:83], v[82:83], v[128:129]
	v_pk_add_f32 v[84:85], v[84:85], v[106:107]
	v_pk_add_f32 v[86:87], v[86:87], v[138:139]
	v_pk_add_f32 v[88:89], v[88:89], v[108:109]
	v_pk_add_f32 v[90:91], v[90:91], v[140:141]
	v_pk_add_f32 v[92:93], v[92:93], v[110:111]
	v_pk_add_f32 v[94:95], v[94:95], v[152:153]
	v_pk_add_f32 v[96:97], v[96:97], v[112:113]
	global_store_dwordx4 v[116:117], v[66:69], off
	global_store_dwordx4 v[116:117], v[70:73], off offset:64
	global_store_dwordx4 v[116:117], v[74:77], off offset:128
	global_store_dwordx4 v[116:117], v[78:81], off offset:192
	global_store_dwordx4 v[116:117], v[82:85], off offset:512
	global_store_dwordx4 v[116:117], v[86:89], off offset:576
	global_store_dwordx4 v[116:117], v[90:93], off offset:640
	global_store_dwordx4 v[116:117], v[94:97], off offset:704
	v_lshl_add_u64 v[208:209], v[118:119], 0, v[210:211]
	global_load_dwordx4 v[192:195], v[208:209], off
	global_load_dwordx4 v[196:199], v[208:209], off offset:64
	v_lshl_add_u64 v[208:209], v[118:119], 0, v[210:211]
	global_load_dwordx4 v[200:203], v[208:209], off offset:256
	global_load_dwordx4 v[204:207], v[208:209], off offset:320
	v_add_u32_e32 v82, 0x90, v132
	v_ashrrev_i32_e32 v83, 31, v82
	v_lshlrev_b64 v[84:85], 12, v[114:115]
	v_lshlrev_b64 v[86:87], 11, v[82:83]
	v_lshl_add_u64 v[84:85], s[24:25], 0, v[84:85]
	v_lshl_add_u64 v[86:87], s[12:13], 0, v[86:87]
	v_lshl_add_u64 v[84:85], v[84:85], 0, v[136:137]
	v_lshl_add_u64 v[86:87], v[86:87], 0, v[134:135]
	s_waitcnt vmcnt(3)
	v_permlane16_swap_b32_e32 v192, v194
	v_permlane16_swap_b32_e32 v193, v195
	v_lshlrev_b32_e32 v88, 16, v192
	v_and_b32_e32 v89, 0xffff0000, v192
	v_lshlrev_b32_e32 v66, 16, v193
	v_and_b32_e32 v67, 0xffff0000, v193
	s_waitcnt vmcnt(3)
	v_lshlrev_b32_e32 v90, 16, v194
	v_and_b32_e32 v91, 0xffff0000, v194
	v_lshlrev_b32_e32 v68, 16, v195
	v_and_b32_e32 v69, 0xffff0000, v195
	s_waitcnt vmcnt(2)
	v_permlane16_swap_b32_e32 v196, v198
	v_permlane16_swap_b32_e32 v197, v199
	v_lshlrev_b32_e32 v92, 16, v196
	v_and_b32_e32 v93, 0xffff0000, v196
	v_lshlrev_b32_e32 v70, 16, v197
	v_and_b32_e32 v71, 0xffff0000, v197
	s_waitcnt vmcnt(2)
	v_lshlrev_b32_e32 v94, 16, v198
	v_and_b32_e32 v95, 0xffff0000, v198
	v_lshlrev_b32_e32 v72, 16, v199
	v_and_b32_e32 v73, 0xffff0000, v199
	s_waitcnt vmcnt(1)
	v_permlane16_swap_b32_e32 v200, v202
	v_permlane16_swap_b32_e32 v201, v203
	v_lshlrev_b32_e32 v96, 16, v200
	v_and_b32_e32 v97, 0xffff0000, v200
	v_lshlrev_b32_e32 v74, 16, v201
	v_and_b32_e32 v75, 0xffff0000, v201
	s_waitcnt vmcnt(1)
	v_lshlrev_b32_e32 v98, 16, v202
	v_and_b32_e32 v99, 0xffff0000, v202
	v_lshlrev_b32_e32 v76, 16, v203
	v_and_b32_e32 v77, 0xffff0000, v203
	s_waitcnt vmcnt(0)
	v_permlane16_swap_b32_e32 v204, v206
	v_permlane16_swap_b32_e32 v205, v207
	v_lshlrev_b32_e32 v100, 16, v204
	v_and_b32_e32 v101, 0xffff0000, v204
	v_lshlrev_b32_e32 v78, 16, v205
	v_and_b32_e32 v79, 0xffff0000, v205
	s_waitcnt vmcnt(0)
	v_lshlrev_b32_e32 v102, 16, v206
	v_and_b32_e32 v103, 0xffff0000, v206
	v_lshlrev_b32_e32 v80, 16, v207
	v_and_b32_e32 v81, 0xffff0000, v207
	v_pk_add_f32 v[34:35], v[34:35], v[88:89]
	v_pk_add_f32 v[36:37], v[36:37], v[66:67]
	v_pk_add_f32 v[38:39], v[38:39], v[90:91]
	v_pk_add_f32 v[40:41], v[40:41], v[68:69]
	v_pk_add_f32 v[42:43], v[42:43], v[92:93]
	v_pk_add_f32 v[44:45], v[44:45], v[70:71]
	v_pk_add_f32 v[46:47], v[46:47], v[94:95]
	v_pk_add_f32 v[48:49], v[48:49], v[72:73]
	v_pk_add_f32 v[50:51], v[50:51], v[96:97]
	v_pk_add_f32 v[52:53], v[52:53], v[74:75]
	v_pk_add_f32 v[54:55], v[54:55], v[98:99]
	v_pk_add_f32 v[56:57], v[56:57], v[76:77]
	v_pk_add_f32 v[58:59], v[58:59], v[100:101]
	v_pk_add_f32 v[60:61], v[60:61], v[78:79]
	v_pk_add_f32 v[62:63], v[62:63], v[102:103]
	v_pk_add_f32 v[64:65], v[64:65], v[80:81]
	global_store_dwordx4 v[84:85], v[34:37], off
	global_store_dwordx4 v[84:85], v[38:41], off offset:64
	global_store_dwordx4 v[84:85], v[42:45], off offset:128
	global_store_dwordx4 v[84:85], v[46:49], off offset:192
	global_store_dwordx4 v[84:85], v[50:53], off offset:512
	global_store_dwordx4 v[84:85], v[54:57], off offset:576
	global_store_dwordx4 v[84:85], v[58:61], off offset:640
	global_store_dwordx4 v[84:85], v[62:65], off offset:704
	v_lshl_add_u64 v[208:209], v[86:87], 0, v[210:211]
	global_load_dwordx4 v[192:195], v[208:209], off
	global_load_dwordx4 v[196:199], v[208:209], off offset:64
	v_lshl_add_u64 v[208:209], v[86:87], 0, v[210:211]
	global_load_dwordx4 v[200:203], v[208:209], off offset:256
	global_load_dwordx4 v[204:207], v[208:209], off offset:320
	v_lshlrev_b64 v[50:51], 12, v[82:83]
	v_lshl_add_u64 v[50:51], s[24:25], 0, v[50:51]
	v_lshl_add_u64 v[50:51], v[50:51], 0, v[136:137]
	s_waitcnt vmcnt(3)
	v_permlane16_swap_b32_e32 v192, v194
	v_permlane16_swap_b32_e32 v193, v195
	v_lshlrev_b32_e32 v52, 16, v192
	v_and_b32_e32 v53, 0xffff0000, v192
	v_lshlrev_b32_e32 v34, 16, v193
	v_and_b32_e32 v35, 0xffff0000, v193
	s_waitcnt vmcnt(3)
	v_lshlrev_b32_e32 v54, 16, v194
	v_and_b32_e32 v55, 0xffff0000, v194
	v_lshlrev_b32_e32 v36, 16, v195
	v_and_b32_e32 v37, 0xffff0000, v195
	s_waitcnt vmcnt(2)
	v_permlane16_swap_b32_e32 v196, v198
	v_permlane16_swap_b32_e32 v197, v199
	v_lshlrev_b32_e32 v56, 16, v196
	v_and_b32_e32 v57, 0xffff0000, v196
	v_lshlrev_b32_e32 v38, 16, v197
	v_and_b32_e32 v39, 0xffff0000, v197
	s_waitcnt vmcnt(2)
	v_lshlrev_b32_e32 v58, 16, v198
	v_and_b32_e32 v59, 0xffff0000, v198
	v_lshlrev_b32_e32 v40, 16, v199
	v_and_b32_e32 v41, 0xffff0000, v199
	s_waitcnt vmcnt(1)
	v_permlane16_swap_b32_e32 v200, v202
	v_permlane16_swap_b32_e32 v201, v203
	v_lshlrev_b32_e32 v60, 16, v200
	v_and_b32_e32 v61, 0xffff0000, v200
	v_lshlrev_b32_e32 v42, 16, v201
	v_and_b32_e32 v43, 0xffff0000, v201
	s_waitcnt vmcnt(1)
	v_lshlrev_b32_e32 v62, 16, v202
	v_and_b32_e32 v63, 0xffff0000, v202
	v_lshlrev_b32_e32 v44, 16, v203
	v_and_b32_e32 v45, 0xffff0000, v203
	s_waitcnt vmcnt(0)
	v_permlane16_swap_b32_e32 v204, v206
	v_permlane16_swap_b32_e32 v205, v207
	v_lshlrev_b32_e32 v64, 16, v204
	v_and_b32_e32 v65, 0xffff0000, v204
	v_lshlrev_b32_e32 v46, 16, v205
	v_and_b32_e32 v47, 0xffff0000, v205
	s_waitcnt vmcnt(0)
	v_lshlrev_b32_e32 v66, 16, v206
	v_and_b32_e32 v67, 0xffff0000, v206
	v_lshlrev_b32_e32 v48, 16, v207
	v_and_b32_e32 v49, 0xffff0000, v207
	v_pk_add_f32 v[2:3], v[2:3], v[52:53]
	v_pk_add_f32 v[4:5], v[4:5], v[34:35]
	v_pk_add_f32 v[6:7], v[6:7], v[54:55]
	v_pk_add_f32 v[8:9], v[8:9], v[36:37]
	v_pk_add_f32 v[10:11], v[10:11], v[56:57]
	v_pk_add_f32 v[12:13], v[12:13], v[38:39]
	v_pk_add_f32 v[14:15], v[14:15], v[58:59]
	v_pk_add_f32 v[16:17], v[16:17], v[40:41]
	v_pk_add_f32 v[18:19], v[18:19], v[60:61]
	v_pk_add_f32 v[20:21], v[20:21], v[42:43]
	v_pk_add_f32 v[26:27], v[26:27], v[62:63]
	v_pk_add_f32 v[28:29], v[28:29], v[44:45]
	v_pk_add_f32 v[30:31], v[30:31], v[64:65]
	v_pk_add_f32 v[32:33], v[32:33], v[46:47]
	v_pk_add_f32 v[22:23], v[22:23], v[66:67]
	v_pk_add_f32 v[24:25], v[24:25], v[48:49]
	global_store_dwordx4 v[50:51], v[2:5], off
	global_store_dwordx4 v[50:51], v[6:9], off offset:64
	global_store_dwordx4 v[50:51], v[10:13], off offset:128
	global_store_dwordx4 v[50:51], v[14:17], off offset:192
	global_store_dwordx4 v[50:51], v[18:21], off offset:512
	global_store_dwordx4 v[50:51], v[26:29], off offset:576
	global_store_dwordx4 v[50:51], v[30:33], off offset:640
	global_store_dwordx4 v[50:51], v[22:25], off offset:704
	s_load_dword s22, s[0:1], 0x0
	s_waitcnt lgkmcnt(0)
	s_add_i32 s10, s22, s10
	s_cmpk_lt_i32 s10, 0x100
	s_cbranch_scc0 .LBB0_401
